# adaLN-RMSNorm loops: bf16 output rows stored with dwordx4 (neighbouring lanes exchange halves via DPP quad_perm; even lanes write chunk 2p, odd lanes chunk 2p+1) instead of dwordx2
# speedup vs baseline: 1.0020x; 1.0020x over previous
; DI unsigned pk2(float lo, float hi) { f32x2 v = {lo, hi}; bf16x2_t b = __builtin_convertvector(v, bf16x2_t); return __builtin_bit_cast(unsigned, b); }
; DI void normmod_phase(const float* xl, const float* xc, const float* g, const float* modl  , int cshift, int cscale, bf16_t* H, int nrows, int gw, int NGW, int lane,
;                       const float* part  , const float* pgate  , float* xc_out) {
;     auto ld = [&](const int row, f32x4 (&v)[4]) __attribute__((always_inline)) -> float {
;         const bool lat = row < ML;
;         const float* xr = lat ? xl + (size_t)row * D : xc + (size_t)(row - ML) * D;
;         float ss = 0.f;
; #pragma unroll
;         for (int j = 0; j < 4; ++j) { v[j] = *(const f32x4*)(xr + lane * 4 + 256 * j);
;             if (part && !lat) {
;                 const size_t po = (size_t)(row - ML) * D + lane * 4 + 256 * j;
;                 const f32x4 p0 = *(const f32x4*)(part + po), p1 = *(const f32x4*)(part + (size_t)MC * D + po), p2 = *(const f32x4*)(part + (size_t)2 * MC * D + po), p3 = *(const f32x4*)(part + (size_t)3 * MC * D + po);
;                 v[j] = v[j] + *(const f32x4*)(pgate + lane * 4 + 256 * j) * ((p0 + p1) + (p2 + p3));
;                 *(f32x4*)(xc_out + po) = v[j]; }
;             ss += (v[j][0] * v[j][0] + v[j][1] * v[j][1]) + (v[j][2] * v[j][2] + v[j][3] * v[j][3]); }
;         return ss; };
;     auto st = [&](const int row, const f32x4 (&v)[4], const float rs) __attribute__((always_inline)) {
;         const float* mp = modl + (size_t)((row < ML) ? (row >> 12) : 16) * 6144;
; #pragma unroll
;         for (int j = 0; j < 4; ++j) { const int c = lane * 4 + 256 * j;
;             const f32x4 gg = *(const f32x4*)(g + c), sh = *(const f32x4*)(mp + cshift * 1024 + c), scl = *(const f32x4*)(mp + cscale * 1024 + c);
;             const f32x4 y = (v[j] * rs) * gg * (scl + 1.f) + sh;
;             u32x2 o; o.x = pk2(y[0], y[1]); o.y = pk2(y[2], y[3]);
;             *(u32x2*)(H + (size_t)row * D + c) = o; } };
;     for (int row = gw * 4; row < (nrows < ML ? nrows : ML); row += NGW * 4) {
;         f32x4 vA[4], vB[4], vC[4], vD[4];
;         float sA = ld(row, vA), sB = ld(row + 1, vB), sC = ld(row + 2, vC), sD = ld(row + 3, vD);
.LBB0_314:
	s_lshl_b32 s8, s69, 12
	s_add_u32 s4, s4, s8
	s_addc_u32 s5, s5, 0
	s_add_u32 s8, s84, 0x312dc000
	v_readlane_b32 s56, v253, 23
	s_addc_u32 s9, s85, 0
	v_readlane_b32 s57, v253, 24
	s_and_b64 s[26:27], s[56:57], exec
	s_cselect_b32 s25, 0, s8
	s_cselect_b32 s20, 0, s9
	s_add_u32 s38, s25, 0x1000000
	s_addc_u32 s39, s20, 0
	s_add_u32 s40, s25, 0x2000000
	s_addc_u32 s41, s20, 0
	s_add_u32 s42, s25, 0x3000000
	v_lshlrev_b32_e32 v69, 2, v152
	v_lshlrev_b32_e32 v74, 4, v152
	v_mov_b32_e32 v75, v149
	s_addc_u32 s43, s20, 0
	v_lshl_add_u64 v[0:1], s[16:17], 0, v[74:75]
	s_mov_b64 s[26:27], 0x62000
	v_or_b32_e32 v68, 0x100, v69
	v_or_b32_e32 v70, 0x200, v69
	v_or_b32_e32 v72, 0x300, v69
	s_cmpk_gt_i32 s36, 0x3fff
	v_lshl_add_u64 v[64:65], v[0:1], 0, s[26:27]
	v_lshl_add_u64 v[66:67], s[4:5], 0, v[74:75]
	v_lshlrev_b32_e32 v71, 2, v68
	v_lshlrev_b32_e32 v73, 2, v70
	v_lshlrev_b32_e32 v80, 2, v72
	s_cbranch_scc1 .LBB0_353
	v_xor_b32_e32 v0, 1, v210
	v_cmp_lt_i32_e32 vcc, v0, v250
	s_lshl_b32 s5, s96, 5
	s_lshl_b32 s20, s37, 2
	v_cndmask_b32_e32 v0, v210, v0, vcc
	v_lshlrev_b32_e32 v81, 2, v0
	v_xor_b32_e32 v0, 2, v210
	v_cmp_lt_i32_e32 vcc, v0, v250
	s_lshl_b32 s4, s36, 2
	s_add_i32 s5, s5, s20
	v_cndmask_b32_e32 v0, v210, v0, vcc
	v_cmp_lt_i32_e32 vcc, v251, v250
	v_lshlrev_b32_e32 v82, 2, v0
	s_add_i32 s20, s5, 0xffff0001
	v_cndmask_b32_e32 v0, v210, v251, vcc
	v_lshlrev_b32_e32 v83, 2, v0
	v_xor_b32_e32 v0, 8, v210
	s_ashr_i32 s5, s4, 31
	s_lshl_b32 s26, s33, 5
	v_cmp_lt_i32_e32 vcc, v0, v250
	s_lshl_b64 s[30:31], s[4:5], 12
	s_add_u32 s44, s10, s30
	v_cndmask_b32_e32 v0, v210, v0, vcc
	v_lshlrev_b32_e32 v84, 2, v0
	v_xor_b32_e32 v0, 16, v210
	s_addc_u32 s45, s11, s31
	s_ashr_i32 s27, s26, 31
	v_cmp_lt_i32_e32 vcc, v0, v250
	s_lshl_b64 s[46:47], s[26:27], 12
	s_lshl_b64 s[4:5], s[4:5], 11
	v_readlane_b32 s12, v254, 26
	v_cndmask_b32_e32 v0, v210, v0, vcc
	s_add_u32 s25, s12, s78
	v_readlane_b32 s12, v254, 27
	v_lshlrev_b32_e32 v85, 2, v0
	v_xor_b32_e32 v0, 32, v210
	s_addc_u32 s30, s12, s79
	v_cmp_lt_i32_e32 vcc, v0, v250
	s_add_u32 s4, s25, s4
	v_lshlrev_b32_e32 v148, 3, v152
	v_cndmask_b32_e32 v0, v210, v0, vcc
	s_addc_u32 s5, s30, s5
	v_lshlrev_b32_e32 v86, 2, v0
	v_lshl_add_u64 v[76:77], s[4:5], 0, v[148:149]
	s_lshl_b64 s[48:49], s[26:27], 11
	global_load_dwordx4 v[156:159], v[66:67], off
	global_load_dwordx4 v[160:163], v[66:67], off offset:1024
	global_load_dwordx4 v[164:167], v[66:67], off offset:2048
	global_load_dwordx4 v[168:171], v[66:67], off offset:3072
	s_add_u32 s4, s44, 0x1000
	s_addc_u32 s5, s45, 0
	s_add_u32 s34, s44, 0x2000
	s_addc_u32 s35, s45, 0
	s_add_u32 s54, s44, 0x3000
	s_addc_u32 s55, s45, 0
	global_load_dwordx4 v[0:3], v74, s[44:45] nt
	global_load_dwordx4 v[4:7], v74, s[44:45] offset:1024 nt
	global_load_dwordx4 v[8:11], v74, s[44:45] offset:2048 nt
	global_load_dwordx4 v[12:15], v74, s[44:45] offset:3072 nt
	global_load_dwordx4 v[16:19], v74, s[4:5] nt
	global_load_dwordx4 v[20:23], v74, s[4:5] offset:1024 nt
	global_load_dwordx4 v[24:27], v74, s[4:5] offset:2048 nt
	global_load_dwordx4 v[28:31], v74, s[4:5] offset:3072 nt
	global_load_dwordx4 v[32:35], v74, s[34:35] nt
	global_load_dwordx4 v[36:39], v74, s[34:35] offset:1024 nt
	global_load_dwordx4 v[40:43], v74, s[34:35] offset:2048 nt
	global_load_dwordx4 v[44:47], v74, s[34:35] offset:3072 nt
	global_load_dwordx4 v[48:51], v74, s[54:55] nt
	global_load_dwordx4 v[52:55], v74, s[54:55] offset:1024 nt
	global_load_dwordx4 v[56:59], v74, s[54:55] offset:2048 nt
	global_load_dwordx4 v[60:63], v74, s[54:55] offset:3072 nt
	v_bfe_u32 v200, v74, 4, 1
	v_cmp_eq_u32_e64 s[98:99], 0, v200
	v_mul_u32_u24_e32 v200, 0x1f8, v200
	v_mov_b32_e32 v201, 0
	v_lshl_add_u64 v[76:77], v[76:77], 0, v[200:201]
	s_branch .LBB0_317
.LBB0_317:
	s_add_i32 s30, s20, 0xffff
	s_ashr_i32 s30, s30, 12
	s_mul_hi_i32 s31, s30, 0x6000
	s_mulk_i32 s30, 0x6000
	s_add_u32 s50, s16, s30
	s_addc_u32 s51, s17, s31
	s_add_u32 s50, s50, 0x3000
	s_addc_u32 s51, s51, 0
	s_add_u32 s52, s50, 0x1000
	s_addc_u32 s53, s51, 0
	global_load_dwordx4 v[110:113], v74, s[50:51]
	global_load_dwordx4 v[114:117], v74, s[50:51] offset:1024
	global_load_dwordx4 v[118:121], v74, s[50:51] offset:2048
	global_load_dwordx4 v[122:125], v74, s[50:51] offset:3072
	global_load_dwordx4 v[126:129], v74, s[52:53]
	global_load_dwordx4 v[130:133], v74, s[52:53] offset:1024
	global_load_dwordx4 v[134:137], v74, s[52:53] offset:2048
	global_load_dwordx4 v[138:141], v74, s[52:53] offset:3072
	s_add_i32 s27, s20, s26
	s_add_i32 s27, s27, 0xffff
	s_cmp_gt_i32 s27, 0xffff
	s_cselect_b32 s30, 0, s46
	s_cselect_b32 s31, 0, s47
	s_add_u32 s44, s44, s30
	s_addc_u32 s45, s45, s31
	s_add_u32 s4, s44, 0x1000
	s_addc_u32 s5, s45, 0
	s_add_u32 s34, s44, 0x2000
	s_addc_u32 s35, s45, 0
	s_add_u32 s54, s44, 0x3000
	s_addc_u32 s55, s45, 0
	s_mov_b32 s30, 0xfffff000
	s_mov_b32 s31, -1
	v_mov_b32_e32 v178, s68
	v_lshl_add_u64 v[198:199], v[76:77], 0, s[30:31]
	s_waitcnt vmcnt(20)
	v_mul_f32_e32 v176, v1, v1
	v_mul_f32_e32 v177, v3, v3
	v_fmac_f32_e32 v176, v0, v0
	v_fmac_f32_e32 v177, v2, v2
	v_add_f32_e32 v172, v176, v177
	v_mul_f32_e32 v176, v5, v5
	v_mul_f32_e32 v177, v7, v7
	v_fmac_f32_e32 v176, v4, v4
	v_fmac_f32_e32 v177, v6, v6
	v_add_f32_e32 v176, v176, v177
	v_add_f32_e32 v172, v172, v176
	v_mul_f32_e32 v176, v9, v9
	v_mul_f32_e32 v177, v11, v11
	v_fmac_f32_e32 v176, v8, v8
	v_fmac_f32_e32 v177, v10, v10
	v_add_f32_e32 v176, v176, v177
	v_add_f32_e32 v172, v172, v176
	v_mul_f32_e32 v176, v13, v13
	v_mul_f32_e32 v177, v15, v15
	v_fmac_f32_e32 v176, v12, v12
	v_fmac_f32_e32 v177, v14, v14
	v_add_f32_e32 v176, v176, v177
	v_add_f32_e32 v172, v172, v176
	s_waitcnt vmcnt(16)
; DI void normmod_phase(const float* xl, const float* xc, const float* g, const float* modl  , int cshift, int cscale, bf16_t* H, int nrows, int gw, int NGW, int lane,
;                       const float* part  , const float* pgate  , float* xc_out) {
;     auto ld = [&](const int row, f32x4 (&v)[4]) __attribute__((always_inline)) -> float {
;         const bool lat = row < ML;
;         const float* xr = lat ? xl + (size_t)row * D : xc + (size_t)(row - ML) * D;
;         float ss = 0.f;
; #pragma unroll
;         for (int j = 0; j < 4; ++j) { v[j] = *(const f32x4*)(xr + lane * 4 + 256 * j);
;             if (part && !lat) {
;                 const size_t po = (size_t)(row - ML) * D + lane * 4 + 256 * j;
;                 const f32x4 p0 = *(const f32x4*)(part + po), p1 = *(const f32x4*)(part + (size_t)MC * D + po), p2 = *(const f32x4*)(part + (size_t)2 * MC * D + po), p3 = *(const f32x4*)(part + (size_t)3 * MC * D + po);
;                 v[j] = v[j] + *(const f32x4*)(pgate + lane * 4 + 256 * j) * ((p0 + p1) + (p2 + p3));
;                 *(f32x4*)(xc_out + po) = v[j]; }
;             ss += (v[j][0] * v[j][0] + v[j][1] * v[j][1]) + (v[j][2] * v[j][2] + v[j][3] * v[j][3]); }
;         return ss; };
;     auto st = [&](const int row, const f32x4 (&v)[4], const float rs) __attribute__((always_inline)) {
;         const float* mp = modl + (size_t)((row < ML) ? (row >> 12) : 16) * 6144;
; #pragma unroll
;         for (int j = 0; j < 4; ++j) { const int c = lane * 4 + 256 * j;
;             const f32x4 gg = *(const f32x4*)(g + c), sh = *(const f32x4*)(mp + cshift * 1024 + c), scl = *(const f32x4*)(mp + cscale * 1024 + c);
;             const f32x4 y = (v[j] * rs) * gg * (scl + 1.f) + sh;
;             u32x2 o; o.x = pk2(y[0], y[1]); o.y = pk2(y[2], y[3]);
;             *(u32x2*)(H + (size_t)row * D + c) = o; } };
;     for (int row = gw * 4; row < (nrows < ML ? nrows : ML); row += NGW * 4) {
;         f32x4 vA[4], vB[4], vC[4], vD[4];
;         float sA = ld(row, vA), sB = ld(row + 1, vB), sC = ld(row + 2, vC), sD = ld(row + 3, vD);
; #pragma unroll
;         for (int o = 1; o < 64; o <<= 1) { sA += __shfl_xor(sA, o); sB += __shfl_xor(sB, o); sC += __shfl_xor(sC, o); sD += __shfl_xor(sD, o); }
;         st(row, vA, rsqrtf(sA * (1.f / D) + EPS)); st(row + 1, vB, rsqrtf(sB * (1.f / D) + EPS));
	v_mul_f32_e32 v176, v17, v17
	v_mul_f32_e32 v177, v19, v19
	v_fmac_f32_e32 v176, v16, v16
	v_fmac_f32_e32 v177, v18, v18
	v_add_f32_e32 v173, v176, v177
	v_mul_f32_e32 v176, v21, v21
	v_mul_f32_e32 v177, v23, v23
	v_fmac_f32_e32 v176, v20, v20
	v_fmac_f32_e32 v177, v22, v22
	v_add_f32_e32 v176, v176, v177
	v_add_f32_e32 v173, v173, v176
	v_mul_f32_e32 v176, v25, v25
	v_mul_f32_e32 v177, v27, v27
	v_fmac_f32_e32 v176, v24, v24
	v_fmac_f32_e32 v177, v26, v26
	v_add_f32_e32 v176, v176, v177
	v_add_f32_e32 v173, v173, v176
	v_mul_f32_e32 v176, v29, v29
	v_mul_f32_e32 v177, v31, v31
	v_fmac_f32_e32 v176, v28, v28
	v_fmac_f32_e32 v177, v30, v30
	v_add_f32_e32 v176, v176, v177
	v_add_f32_e32 v173, v173, v176
	s_waitcnt vmcnt(12)
	v_mul_f32_e32 v176, v33, v33
	v_mul_f32_e32 v177, v35, v35
	v_fmac_f32_e32 v176, v32, v32
	v_fmac_f32_e32 v177, v34, v34
	v_add_f32_e32 v174, v176, v177
	v_mul_f32_e32 v176, v37, v37
	v_mul_f32_e32 v177, v39, v39
	v_fmac_f32_e32 v176, v36, v36
	v_fmac_f32_e32 v177, v38, v38
	v_add_f32_e32 v176, v176, v177
	v_add_f32_e32 v174, v174, v176
	v_mul_f32_e32 v176, v41, v41
	v_mul_f32_e32 v177, v43, v43
	v_fmac_f32_e32 v176, v40, v40
	v_fmac_f32_e32 v177, v42, v42
	v_add_f32_e32 v176, v176, v177
	v_add_f32_e32 v174, v174, v176
	v_mul_f32_e32 v176, v45, v45
	v_mul_f32_e32 v177, v47, v47
	v_fmac_f32_e32 v176, v44, v44
	v_fmac_f32_e32 v177, v46, v46
	v_add_f32_e32 v176, v176, v177
	v_add_f32_e32 v174, v174, v176
	s_waitcnt vmcnt(8)
	v_mul_f32_e32 v176, v49, v49
	v_mul_f32_e32 v177, v51, v51
	v_fmac_f32_e32 v176, v48, v48
	v_fmac_f32_e32 v177, v50, v50
	v_add_f32_e32 v175, v176, v177
	v_mul_f32_e32 v176, v53, v53
	v_mul_f32_e32 v177, v55, v55
	v_fmac_f32_e32 v176, v52, v52
	v_fmac_f32_e32 v177, v54, v54
	v_add_f32_e32 v176, v176, v177
	v_add_f32_e32 v175, v175, v176
	v_mul_f32_e32 v176, v57, v57
	v_mul_f32_e32 v177, v59, v59
	v_fmac_f32_e32 v176, v56, v56
	v_fmac_f32_e32 v177, v58, v58
	v_add_f32_e32 v176, v176, v177
	v_add_f32_e32 v175, v175, v176
	v_mul_f32_e32 v176, v61, v61
	v_mul_f32_e32 v177, v63, v63
	v_fmac_f32_e32 v176, v60, v60
	v_fmac_f32_e32 v177, v62, v62
	v_add_f32_e32 v176, v176, v177
	v_add_f32_e32 v175, v175, v176
	ds_bpermute_b32 v184, v81, v172
	ds_bpermute_b32 v185, v81, v173
	ds_bpermute_b32 v186, v81, v174
	ds_bpermute_b32 v187, v81, v175
	s_waitcnt lgkmcnt(0)
	v_pk_add_f32 v[172:173], v[172:173], v[184:185]
	v_pk_add_f32 v[174:175], v[174:175], v[186:187]
	ds_bpermute_b32 v184, v82, v172
	ds_bpermute_b32 v185, v82, v173
	ds_bpermute_b32 v186, v82, v174
	ds_bpermute_b32 v187, v82, v175
	s_waitcnt lgkmcnt(0)
	v_pk_add_f32 v[172:173], v[172:173], v[184:185]
	v_pk_add_f32 v[174:175], v[174:175], v[186:187]
	ds_bpermute_b32 v184, v83, v172
	ds_bpermute_b32 v185, v83, v173
	ds_bpermute_b32 v186, v83, v174
	ds_bpermute_b32 v187, v83, v175
	s_waitcnt lgkmcnt(0)
	v_pk_add_f32 v[172:173], v[172:173], v[184:185]
	v_pk_add_f32 v[174:175], v[174:175], v[186:187]
	ds_bpermute_b32 v184, v84, v172
	ds_bpermute_b32 v185, v84, v173
	ds_bpermute_b32 v186, v84, v174
	ds_bpermute_b32 v187, v84, v175
	s_waitcnt lgkmcnt(0)
	v_pk_add_f32 v[172:173], v[172:173], v[184:185]
	v_pk_add_f32 v[174:175], v[174:175], v[186:187]
	ds_bpermute_b32 v184, v85, v172
	ds_bpermute_b32 v185, v85, v173
	ds_bpermute_b32 v186, v85, v174
	ds_bpermute_b32 v187, v85, v175
	s_waitcnt lgkmcnt(0)
	v_pk_add_f32 v[172:173], v[172:173], v[184:185]
	v_pk_add_f32 v[174:175], v[174:175], v[186:187]
	ds_bpermute_b32 v184, v86, v172
	ds_bpermute_b32 v185, v86, v173
	ds_bpermute_b32 v186, v86, v174
	ds_bpermute_b32 v187, v86, v175
	s_waitcnt lgkmcnt(0)
	v_pk_add_f32 v[172:173], v[172:173], v[184:185]
	v_pk_add_f32 v[174:175], v[174:175], v[186:187]
	v_fma_f32 v172, v172, s66, v178
	v_fma_f32 v173, v173, s66, v178
	v_fma_f32 v174, v174, s66, v178
	v_fma_f32 v175, v175, s66, v178
	v_mul_f32_e32 v184, 0x4b800000, v172
	v_mul_f32_e32 v185, 0x4b800000, v173
	v_mul_f32_e32 v186, 0x4b800000, v174
	v_mul_f32_e32 v187, 0x4b800000, v175
	s_waitcnt vmcnt(0)
	v_cmp_gt_f32_e64 s[50:51], s62, v172
	v_cmp_gt_f32_e64 s[52:53], s62, v173
	v_cmp_gt_f32_e64 s[30:31], s62, v174
	v_cmp_gt_f32_e32 vcc, s62, v175
	s_nop 1
	v_cndmask_b32_e64 v172, v172, v184, s[50:51]
	v_cndmask_b32_e64 v173, v173, v185, s[52:53]
	v_cndmask_b32_e64 v174, v174, v186, s[30:31]
	v_cndmask_b32_e32 v175, v175, v187, vcc
	v_rsq_f32_e32 v172, v172
	v_rsq_f32_e32 v173, v173
	v_rsq_f32_e32 v174, v174
	v_rsq_f32_e32 v175, v175
	s_nop 0
	v_mul_f32_e32 v184, 0x45800000, v172
	v_mul_f32_e32 v185, 0x45800000, v173
	v_mul_f32_e32 v186, 0x45800000, v174
	v_mul_f32_e32 v187, 0x45800000, v175
	v_cndmask_b32_e64 v188, v172, v184, s[50:51]
	v_cndmask_b32_e64 v190, v173, v185, s[52:53]
	v_cndmask_b32_e64 v192, v174, v186, s[30:31]
	v_cndmask_b32_e32 v194, v175, v187, vcc
	v_pk_add_f32 v[126:127], v[126:127], 1.0 op_sel_hi:[1,0]
	v_pk_add_f32 v[128:129], v[128:129], 1.0 op_sel_hi:[1,0]
	v_pk_add_f32 v[130:131], v[130:131], 1.0 op_sel_hi:[1,0]
	v_pk_add_f32 v[132:133], v[132:133], 1.0 op_sel_hi:[1,0]
	v_pk_add_f32 v[134:135], v[134:135], 1.0 op_sel_hi:[1,0]
	v_pk_add_f32 v[136:137], v[136:137], 1.0 op_sel_hi:[1,0]
	v_pk_add_f32 v[138:139], v[138:139], 1.0 op_sel_hi:[1,0]
	v_pk_add_f32 v[140:141], v[140:141], 1.0 op_sel_hi:[1,0]
	v_pk_mul_f32 v[0:1], v[0:1], v[188:189] op_sel_hi:[1,0]
	v_pk_mul_f32 v[2:3], v[2:3], v[188:189] op_sel_hi:[1,0]
	v_pk_mul_f32 v[0:1], v[156:157], v[0:1]
	v_pk_mul_f32 v[2:3], v[158:159], v[2:3]
	v_pk_fma_f32 v[0:1], v[126:127], v[0:1], v[110:111]
	v_pk_fma_f32 v[2:3], v[128:129], v[2:3], v[112:113]
	v_pk_mul_f32 v[4:5], v[4:5], v[188:189] op_sel_hi:[1,0]
	v_pk_mul_f32 v[6:7], v[6:7], v[188:189] op_sel_hi:[1,0]
; DI unsigned pk2(float lo, float hi) { f32x2 v = {lo, hi}; bf16x2_t b = __builtin_convertvector(v, bf16x2_t); return __builtin_bit_cast(unsigned, b); }
; DI void normmod_phase(const float* xl, const float* xc, const float* g, const float* modl  , int cshift, int cscale, bf16_t* H, int nrows, int gw, int NGW, int lane,
;                       const float* part  , const float* pgate  , float* xc_out) {
;     ...
;     auto st = [&](const int row, const f32x4 (&v)[4], const float rs) __attribute__((always_inline)) {
;         const float* mp = modl + (size_t)((row < ML) ? (row >> 12) : 16) * 6144;
; #pragma unroll
;         for (int j = 0; j < 4; ++j) { const int c = lane * 4 + 256 * j;
;             const f32x4 gg = *(const f32x4*)(g + c), sh = *(const f32x4*)(mp + cshift * 1024 + c), scl = *(const f32x4*)(mp + cscale * 1024 + c);
;             const f32x4 y = (v[j] * rs) * gg * (scl + 1.f) + sh;
;             u32x2 o; o.x = pk2(y[0], y[1]); o.y = pk2(y[2], y[3]);
;             *(u32x2*)(H + (size_t)row * D + c) = o; } };
	v_pk_mul_f32 v[4:5], v[160:161], v[4:5]
	v_pk_mul_f32 v[6:7], v[162:163], v[6:7]
	v_pk_fma_f32 v[4:5], v[130:131], v[4:5], v[114:115]
	v_pk_fma_f32 v[6:7], v[132:133], v[6:7], v[116:117]
	v_pk_mul_f32 v[8:9], v[8:9], v[188:189] op_sel_hi:[1,0]
	v_pk_mul_f32 v[10:11], v[10:11], v[188:189] op_sel_hi:[1,0]
	v_pk_mul_f32 v[8:9], v[164:165], v[8:9]
	v_pk_mul_f32 v[10:11], v[166:167], v[10:11]
	v_pk_fma_f32 v[8:9], v[134:135], v[8:9], v[118:119]
	v_pk_fma_f32 v[10:11], v[136:137], v[10:11], v[120:121]
	v_pk_mul_f32 v[12:13], v[12:13], v[188:189] op_sel_hi:[1,0]
	v_pk_mul_f32 v[14:15], v[14:15], v[188:189] op_sel_hi:[1,0]
	v_pk_mul_f32 v[12:13], v[168:169], v[12:13]
	v_pk_mul_f32 v[14:15], v[170:171], v[14:15]
	v_pk_fma_f32 v[12:13], v[138:139], v[12:13], v[122:123]
	v_pk_fma_f32 v[14:15], v[140:141], v[14:15], v[124:125]
	v_cvt_pk_bf16_f32 v0, v0, v1
	v_cvt_pk_bf16_f32 v1, v2, v3
	v_cvt_pk_bf16_f32 v4, v4, v5
	v_cvt_pk_bf16_f32 v5, v6, v7
	v_cvt_pk_bf16_f32 v8, v8, v9
	v_cvt_pk_bf16_f32 v9, v10, v11
	v_cvt_pk_bf16_f32 v12, v12, v13
	v_cvt_pk_bf16_f32 v13, v14, v15
	v_mov_b32_dpp v2, v0 quad_perm:[1,0,3,2] row_mask:0xf bank_mask:0xf
	v_mov_b32_dpp v3, v1 quad_perm:[1,0,3,2] row_mask:0xf bank_mask:0xf
	v_mov_b32_dpp v176, v4 quad_perm:[1,0,3,2] row_mask:0xf bank_mask:0xf
	v_mov_b32_dpp v177, v5 quad_perm:[1,0,3,2] row_mask:0xf bank_mask:0xf
	v_cndmask_b32_e64 v2, v4, v2, s[98:99]
	v_cndmask_b32_e64 v3, v5, v3, s[98:99]
	v_cndmask_b32_e64 v0, v176, v0, s[98:99]
	v_cndmask_b32_e64 v1, v177, v1, s[98:99]
	global_store_dwordx4 v[198:199], v[0:3], off offset:-3584
	v_mov_b32_dpp v10, v8 quad_perm:[1,0,3,2] row_mask:0xf bank_mask:0xf
	v_mov_b32_dpp v11, v9 quad_perm:[1,0,3,2] row_mask:0xf bank_mask:0xf
	v_mov_b32_dpp v176, v12 quad_perm:[1,0,3,2] row_mask:0xf bank_mask:0xf
	v_mov_b32_dpp v177, v13 quad_perm:[1,0,3,2] row_mask:0xf bank_mask:0xf
	v_cndmask_b32_e64 v10, v12, v10, s[98:99]
	v_cndmask_b32_e64 v11, v13, v11, s[98:99]
	v_cndmask_b32_e64 v8, v176, v8, s[98:99]
	v_cndmask_b32_e64 v9, v177, v9, s[98:99]
	global_store_dwordx4 v[198:199], v[8:11], off offset:-2560
	global_load_dwordx4 v[0:3], v74, s[44:45] nt
	global_load_dwordx4 v[4:7], v74, s[44:45] offset:1024 nt
	global_load_dwordx4 v[8:11], v74, s[44:45] offset:2048 nt
	global_load_dwordx4 v[12:15], v74, s[44:45] offset:3072 nt
	v_pk_mul_f32 v[16:17], v[16:17], v[190:191] op_sel_hi:[1,0]
	v_pk_mul_f32 v[18:19], v[18:19], v[190:191] op_sel_hi:[1,0]
	v_pk_mul_f32 v[16:17], v[156:157], v[16:17]
	v_pk_mul_f32 v[18:19], v[158:159], v[18:19]
	v_pk_fma_f32 v[16:17], v[126:127], v[16:17], v[110:111]
	v_pk_fma_f32 v[18:19], v[128:129], v[18:19], v[112:113]
	v_pk_mul_f32 v[20:21], v[20:21], v[190:191] op_sel_hi:[1,0]
	v_pk_mul_f32 v[22:23], v[22:23], v[190:191] op_sel_hi:[1,0]
	v_pk_mul_f32 v[20:21], v[160:161], v[20:21]
	v_pk_mul_f32 v[22:23], v[162:163], v[22:23]
	v_pk_fma_f32 v[20:21], v[130:131], v[20:21], v[114:115]
	v_pk_fma_f32 v[22:23], v[132:133], v[22:23], v[116:117]
	v_pk_mul_f32 v[24:25], v[24:25], v[190:191] op_sel_hi:[1,0]
	v_pk_mul_f32 v[26:27], v[26:27], v[190:191] op_sel_hi:[1,0]
	v_pk_mul_f32 v[24:25], v[164:165], v[24:25]
	v_pk_mul_f32 v[26:27], v[166:167], v[26:27]
	v_pk_fma_f32 v[24:25], v[134:135], v[24:25], v[118:119]
	v_pk_fma_f32 v[26:27], v[136:137], v[26:27], v[120:121]
	v_pk_mul_f32 v[28:29], v[28:29], v[190:191] op_sel_hi:[1,0]
	v_pk_mul_f32 v[30:31], v[30:31], v[190:191] op_sel_hi:[1,0]
	v_pk_mul_f32 v[28:29], v[168:169], v[28:29]
	v_pk_mul_f32 v[30:31], v[170:171], v[30:31]
	v_pk_fma_f32 v[28:29], v[138:139], v[28:29], v[122:123]
	v_pk_fma_f32 v[30:31], v[140:141], v[30:31], v[124:125]
	v_cvt_pk_bf16_f32 v16, v16, v17
	v_cvt_pk_bf16_f32 v17, v18, v19
	v_cvt_pk_bf16_f32 v20, v20, v21
	v_cvt_pk_bf16_f32 v21, v22, v23
	v_cvt_pk_bf16_f32 v24, v24, v25
	v_cvt_pk_bf16_f32 v25, v26, v27
	v_cvt_pk_bf16_f32 v28, v28, v29
	v_cvt_pk_bf16_f32 v29, v30, v31
	v_mov_b32_dpp v18, v16 quad_perm:[1,0,3,2] row_mask:0xf bank_mask:0xf
	v_mov_b32_dpp v19, v17 quad_perm:[1,0,3,2] row_mask:0xf bank_mask:0xf
	v_mov_b32_dpp v176, v20 quad_perm:[1,0,3,2] row_mask:0xf bank_mask:0xf
	v_mov_b32_dpp v177, v21 quad_perm:[1,0,3,2] row_mask:0xf bank_mask:0xf
	v_cndmask_b32_e64 v18, v20, v18, s[98:99]
	v_cndmask_b32_e64 v19, v21, v19, s[98:99]
	v_cndmask_b32_e64 v16, v176, v16, s[98:99]
	v_cndmask_b32_e64 v17, v177, v17, s[98:99]
	global_store_dwordx4 v[198:199], v[16:19], off offset:-1536
	v_mov_b32_dpp v26, v24 quad_perm:[1,0,3,2] row_mask:0xf bank_mask:0xf
	v_mov_b32_dpp v27, v25 quad_perm:[1,0,3,2] row_mask:0xf bank_mask:0xf
	v_mov_b32_dpp v176, v28 quad_perm:[1,0,3,2] row_mask:0xf bank_mask:0xf
	v_mov_b32_dpp v177, v29 quad_perm:[1,0,3,2] row_mask:0xf bank_mask:0xf
	v_cndmask_b32_e64 v26, v28, v26, s[98:99]
	v_cndmask_b32_e64 v27, v29, v27, s[98:99]
	v_cndmask_b32_e64 v24, v176, v24, s[98:99]
	v_cndmask_b32_e64 v25, v177, v25, s[98:99]
	global_store_dwordx4 v[198:199], v[24:27], off offset:-512
	global_load_dwordx4 v[16:19], v74, s[4:5] nt
	global_load_dwordx4 v[20:23], v74, s[4:5] offset:1024 nt
	global_load_dwordx4 v[24:27], v74, s[4:5] offset:2048 nt
	global_load_dwordx4 v[28:31], v74, s[4:5] offset:3072 nt
	v_pk_mul_f32 v[32:33], v[32:33], v[192:193] op_sel_hi:[1,0]
	v_pk_mul_f32 v[34:35], v[34:35], v[192:193] op_sel_hi:[1,0]
	v_pk_mul_f32 v[32:33], v[156:157], v[32:33]
	v_pk_mul_f32 v[34:35], v[158:159], v[34:35]
	v_pk_fma_f32 v[32:33], v[126:127], v[32:33], v[110:111]
	v_pk_fma_f32 v[34:35], v[128:129], v[34:35], v[112:113]
; DI unsigned pk2(float lo, float hi) { f32x2 v = {lo, hi}; bf16x2_t b = __builtin_convertvector(v, bf16x2_t); return __builtin_bit_cast(unsigned, b); }
; DI void normmod_phase(const float* xl, const float* xc, const float* g, const float* modl  , int cshift, int cscale, bf16_t* H, int nrows, int gw, int NGW, int lane,
;                       const float* part  , const float* pgate  , float* xc_out) {
;     ...
;     auto st = [&](const int row, const f32x4 (&v)[4], const float rs) __attribute__((always_inline)) {
;         const float* mp = modl + (size_t)((row < ML) ? (row >> 12) : 16) * 6144;
; #pragma unroll
;         for (int j = 0; j < 4; ++j) { const int c = lane * 4 + 256 * j;
;             const f32x4 gg = *(const f32x4*)(g + c), sh = *(const f32x4*)(mp + cshift * 1024 + c), scl = *(const f32x4*)(mp + cscale * 1024 + c);
;             const f32x4 y = (v[j] * rs) * gg * (scl + 1.f) + sh;
;             u32x2 o; o.x = pk2(y[0], y[1]); o.y = pk2(y[2], y[3]);
;             *(u32x2*)(H + (size_t)row * D + c) = o; } };
;     for (int row = gw * 4; row < (nrows < ML ? nrows : ML); row += NGW * 4) {
;         f32x4 vA[4], vB[4], vC[4], vD[4];
;         float sA = ld(row, vA), sB = ld(row + 1, vB), sC = ld(row + 2, vC), sD = ld(row + 3, vD);
; #pragma unroll
;         for (int o = 1; o < 64; o <<= 1) { sA += __shfl_xor(sA, o); sB += __shfl_xor(sB, o); sC += __shfl_xor(sC, o); sD += __shfl_xor(sD, o); }
;         st(row, vA, rsqrtf(sA * (1.f / D) + EPS)); st(row + 1, vB, rsqrtf(sB * (1.f / D) + EPS));
;         st(row + 2, vC, rsqrtf(sC * (1.f / D) + EPS)); st(row + 3, vD, rsqrtf(sD * (1.f / D) + EPS));
	v_pk_mul_f32 v[36:37], v[36:37], v[192:193] op_sel_hi:[1,0]
	v_pk_mul_f32 v[38:39], v[38:39], v[192:193] op_sel_hi:[1,0]
	v_pk_mul_f32 v[36:37], v[160:161], v[36:37]
	v_pk_mul_f32 v[38:39], v[162:163], v[38:39]
	v_pk_fma_f32 v[36:37], v[130:131], v[36:37], v[114:115]
	v_pk_fma_f32 v[38:39], v[132:133], v[38:39], v[116:117]
	v_pk_mul_f32 v[40:41], v[40:41], v[192:193] op_sel_hi:[1,0]
	v_pk_mul_f32 v[42:43], v[42:43], v[192:193] op_sel_hi:[1,0]
	v_pk_mul_f32 v[40:41], v[164:165], v[40:41]
	v_pk_mul_f32 v[42:43], v[166:167], v[42:43]
	v_pk_fma_f32 v[40:41], v[134:135], v[40:41], v[118:119]
	v_pk_fma_f32 v[42:43], v[136:137], v[42:43], v[120:121]
	v_pk_mul_f32 v[44:45], v[44:45], v[192:193] op_sel_hi:[1,0]
	v_pk_mul_f32 v[46:47], v[46:47], v[192:193] op_sel_hi:[1,0]
	v_pk_mul_f32 v[44:45], v[168:169], v[44:45]
	v_pk_mul_f32 v[46:47], v[170:171], v[46:47]
	v_pk_fma_f32 v[44:45], v[138:139], v[44:45], v[122:123]
	v_pk_fma_f32 v[46:47], v[140:141], v[46:47], v[124:125]
	v_cvt_pk_bf16_f32 v32, v32, v33
	v_cvt_pk_bf16_f32 v33, v34, v35
	v_cvt_pk_bf16_f32 v36, v36, v37
	v_cvt_pk_bf16_f32 v37, v38, v39
	v_cvt_pk_bf16_f32 v40, v40, v41
	v_cvt_pk_bf16_f32 v41, v42, v43
	v_cvt_pk_bf16_f32 v44, v44, v45
	v_cvt_pk_bf16_f32 v45, v46, v47
	v_mov_b32_dpp v34, v32 quad_perm:[1,0,3,2] row_mask:0xf bank_mask:0xf
	v_mov_b32_dpp v35, v33 quad_perm:[1,0,3,2] row_mask:0xf bank_mask:0xf
	v_mov_b32_dpp v176, v36 quad_perm:[1,0,3,2] row_mask:0xf bank_mask:0xf
	v_mov_b32_dpp v177, v37 quad_perm:[1,0,3,2] row_mask:0xf bank_mask:0xf
	v_cndmask_b32_e64 v34, v36, v34, s[98:99]
	v_cndmask_b32_e64 v35, v37, v35, s[98:99]
	v_cndmask_b32_e64 v32, v176, v32, s[98:99]
	v_cndmask_b32_e64 v33, v177, v33, s[98:99]
	global_store_dwordx4 v[76:77], v[32:35], off offset:-3584
	v_mov_b32_dpp v42, v40 quad_perm:[1,0,3,2] row_mask:0xf bank_mask:0xf
	v_mov_b32_dpp v43, v41 quad_perm:[1,0,3,2] row_mask:0xf bank_mask:0xf
	v_mov_b32_dpp v176, v44 quad_perm:[1,0,3,2] row_mask:0xf bank_mask:0xf
	v_mov_b32_dpp v177, v45 quad_perm:[1,0,3,2] row_mask:0xf bank_mask:0xf
	v_cndmask_b32_e64 v42, v44, v42, s[98:99]
	v_cndmask_b32_e64 v43, v45, v43, s[98:99]
	v_cndmask_b32_e64 v40, v176, v40, s[98:99]
	v_cndmask_b32_e64 v41, v177, v41, s[98:99]
	global_store_dwordx4 v[76:77], v[40:43], off offset:-2560
	global_load_dwordx4 v[32:35], v74, s[34:35] nt
	global_load_dwordx4 v[36:39], v74, s[34:35] offset:1024 nt
	global_load_dwordx4 v[40:43], v74, s[34:35] offset:2048 nt
	global_load_dwordx4 v[44:47], v74, s[34:35] offset:3072 nt
	v_pk_mul_f32 v[48:49], v[48:49], v[194:195] op_sel_hi:[1,0]
	v_pk_mul_f32 v[50:51], v[50:51], v[194:195] op_sel_hi:[1,0]
	v_pk_mul_f32 v[48:49], v[156:157], v[48:49]
	v_pk_mul_f32 v[50:51], v[158:159], v[50:51]
	v_pk_fma_f32 v[48:49], v[126:127], v[48:49], v[110:111]
	v_pk_fma_f32 v[50:51], v[128:129], v[50:51], v[112:113]
	v_pk_mul_f32 v[52:53], v[52:53], v[194:195] op_sel_hi:[1,0]
	v_pk_mul_f32 v[54:55], v[54:55], v[194:195] op_sel_hi:[1,0]
	v_pk_mul_f32 v[52:53], v[160:161], v[52:53]
	v_pk_mul_f32 v[54:55], v[162:163], v[54:55]
	v_pk_fma_f32 v[52:53], v[130:131], v[52:53], v[114:115]
	v_pk_fma_f32 v[54:55], v[132:133], v[54:55], v[116:117]
	v_pk_mul_f32 v[56:57], v[56:57], v[194:195] op_sel_hi:[1,0]
	v_pk_mul_f32 v[58:59], v[58:59], v[194:195] op_sel_hi:[1,0]
	v_pk_mul_f32 v[56:57], v[164:165], v[56:57]
	v_pk_mul_f32 v[58:59], v[166:167], v[58:59]
	v_pk_fma_f32 v[56:57], v[134:135], v[56:57], v[118:119]
	v_pk_fma_f32 v[58:59], v[136:137], v[58:59], v[120:121]
	v_pk_mul_f32 v[60:61], v[60:61], v[194:195] op_sel_hi:[1,0]
	v_pk_mul_f32 v[62:63], v[62:63], v[194:195] op_sel_hi:[1,0]
	v_pk_mul_f32 v[60:61], v[168:169], v[60:61]
	v_pk_mul_f32 v[62:63], v[170:171], v[62:63]
	v_pk_fma_f32 v[60:61], v[138:139], v[60:61], v[122:123]
	v_pk_fma_f32 v[62:63], v[140:141], v[62:63], v[124:125]
	v_cvt_pk_bf16_f32 v48, v48, v49
	v_cvt_pk_bf16_f32 v49, v50, v51
	v_cvt_pk_bf16_f32 v52, v52, v53
	v_cvt_pk_bf16_f32 v53, v54, v55
	v_cvt_pk_bf16_f32 v56, v56, v57
	v_cvt_pk_bf16_f32 v57, v58, v59
	v_cvt_pk_bf16_f32 v60, v60, v61
	v_cvt_pk_bf16_f32 v61, v62, v63
	v_mov_b32_dpp v50, v48 quad_perm:[1,0,3,2] row_mask:0xf bank_mask:0xf
	v_mov_b32_dpp v51, v49 quad_perm:[1,0,3,2] row_mask:0xf bank_mask:0xf
	v_mov_b32_dpp v176, v52 quad_perm:[1,0,3,2] row_mask:0xf bank_mask:0xf
	v_mov_b32_dpp v177, v53 quad_perm:[1,0,3,2] row_mask:0xf bank_mask:0xf
	v_cndmask_b32_e64 v50, v52, v50, s[98:99]
	v_cndmask_b32_e64 v51, v53, v51, s[98:99]
	v_cndmask_b32_e64 v48, v176, v48, s[98:99]
	v_cndmask_b32_e64 v49, v177, v49, s[98:99]
	global_store_dwordx4 v[76:77], v[48:51], off offset:-1536
	v_mov_b32_dpp v58, v56 quad_perm:[1,0,3,2] row_mask:0xf bank_mask:0xf
	v_mov_b32_dpp v59, v57 quad_perm:[1,0,3,2] row_mask:0xf bank_mask:0xf
	v_mov_b32_dpp v176, v60 quad_perm:[1,0,3,2] row_mask:0xf bank_mask:0xf
	v_mov_b32_dpp v177, v61 quad_perm:[1,0,3,2] row_mask:0xf bank_mask:0xf
	v_cndmask_b32_e64 v58, v60, v58, s[98:99]
	v_cndmask_b32_e64 v59, v61, v59, s[98:99]
	v_cndmask_b32_e64 v56, v176, v56, s[98:99]
	v_cndmask_b32_e64 v57, v177, v57, s[98:99]
	global_store_dwordx4 v[76:77], v[56:59], off offset:-512
	global_load_dwordx4 v[48:51], v74, s[54:55] nt
	global_load_dwordx4 v[52:55], v74, s[54:55] offset:1024 nt
	global_load_dwordx4 v[56:59], v74, s[54:55] offset:2048 nt
	global_load_dwordx4 v[60:63], v74, s[54:55] offset:3072 nt
	s_add_i32 s20, s20, s26
	v_lshl_add_u64 v[76:77], v[76:77], 0, s[48:49]
	s_add_i32 s4, s20, 0xffff
	s_cmp_gt_i32 s4, 0xffff
	s_cbranch_scc0 .LBB0_317
	s_waitcnt vmcnt(0)

; DI unsigned pk2(float lo, float hi) { f32x2 v = {lo, hi}; bf16x2_t b = __builtin_convertvector(v, bf16x2_t); return __builtin_bit_cast(unsigned, b); }
; DI void normmod_phase(const float* xl, const float* xc, const float* g, const float* modl  , int cshift, int cscale, bf16_t* H, int nrows, int gw, int NGW, int lane,
;                       const float* part  , const float* pgate  , float* xc_out) {
;     auto ld = [&](const int row, f32x4 (&v)[4]) __attribute__((always_inline)) -> float {
;         const bool lat = row < ML;
;         const float* xr = lat ? xl + (size_t)row * D : xc + (size_t)(row - ML) * D;
;         float ss = 0.f;
; #pragma unroll
;         for (int j = 0; j < 4; ++j) { v[j] = *(const f32x4*)(xr + lane * 4 + 256 * j);
;             if (part && !lat) {
;                 const size_t po = (size_t)(row - ML) * D + lane * 4 + 256 * j;
;                 const f32x4 p0 = *(const f32x4*)(part + po), p1 = *(const f32x4*)(part + (size_t)MC * D + po), p2 = *(const f32x4*)(part + (size_t)2 * MC * D + po), p3 = *(const f32x4*)(part + (size_t)3 * MC * D + po);
;                 v[j] = v[j] + *(const f32x4*)(pgate + lane * 4 + 256 * j) * ((p0 + p1) + (p2 + p3));
;                 *(f32x4*)(xc_out + po) = v[j]; }
;             ss += (v[j][0] * v[j][0] + v[j][1] * v[j][1]) + (v[j][2] * v[j][2] + v[j][3] * v[j][3]); }
;         return ss; };
;     auto st = [&](const int row, const f32x4 (&v)[4], const float rs) __attribute__((always_inline)) {
;         const float* mp = modl + (size_t)((row < ML) ? (row >> 12) : 16) * 6144;
; #pragma unroll
;         for (int j = 0; j < 4; ++j) { const int c = lane * 4 + 256 * j;
;             const f32x4 gg = *(const f32x4*)(g + c), sh = *(const f32x4*)(mp + cshift * 1024 + c), scl = *(const f32x4*)(mp + cscale * 1024 + c);
;             const f32x4 y = (v[j] * rs) * gg * (scl + 1.f) + sh;
;             u32x2 o; o.x = pk2(y[0], y[1]); o.y = pk2(y[2], y[3]);
;             *(u32x2*)(H + (size_t)row * D + c) = o; } };
;     for (int row = gw * 4; row < (nrows < ML ? nrows : ML); row += NGW * 4) {
;         f32x4 vA[4], vB[4], vC[4], vD[4];
;         float sA = ld(row, vA), sB = ld(row + 1, vB), sC = ld(row + 2, vC), sD = ld(row + 3, vD);
.LBB0_553:
	s_andn2_b64 vcc, exec, s[4:5]
	s_cbranch_vccnz .LBB0_621
	s_lshl_b64 s[4:5], s[78:79], 3
	v_readlane_b32 s6, v253, 5
	v_readlane_b32 s7, v253, 6
	s_add_u32 s4, s6, s4
	s_addc_u32 s5, s7, s5
	s_load_dwordx2 s[4:5], s[4:5], 0x30
	s_lshl_b32 s6, s69, 12
	v_readlane_b32 s54, v253, 28
	v_readlane_b32 s55, v253, 29
	v_lshlrev_b32_e32 v69, 2, v152
	s_waitcnt lgkmcnt(0)
	s_add_u32 s4, s4, s6
	v_readlane_b32 s6, v253, 23
	s_addc_u32 s5, s5, 0
	v_readlane_b32 s7, v253, 24
	s_and_b64 s[6:7], s[6:7], exec
	s_cselect_b32 s23, 0, 0x15400000
	s_add_u32 s6, s84, 0x312dc000
	s_addc_u32 s7, s85, 0
	s_and_b64 s[8:9], s[54:55], exec
	s_cselect_b32 s24, 0, s6
	s_cselect_b32 s20, 0, s7
	s_add_u32 s8, s24, 0x1000000
	s_addc_u32 s9, s20, 0
	s_add_u32 s38, s24, 0x2000000
	s_addc_u32 s39, s20, 0
	s_add_u32 s40, s24, 0x3000000
	s_addc_u32 s41, s20, 0
	v_lshlrev_b32_e32 v76, 4, v152
	v_mov_b32_e32 v77, v149
	v_or_b32_e32 v68, 0x100, v69
	v_or_b32_e32 v70, 0x200, v69
	v_or_b32_e32 v72, 0x300, v69
	s_mov_b32 s56, s36
	s_cmpk_gt_i32 s36, 0x3fff
	v_lshl_add_u64 v[64:65], s[16:17], 0, v[76:77]
	v_lshl_add_u64 v[66:67], s[4:5], 0, v[76:77]
	v_lshlrev_b32_e32 v74, 3, v152
	v_lshlrev_b32_e32 v71, 2, v68
	v_lshlrev_b32_e32 v73, 2, v70
	v_lshlrev_b32_e32 v82, 2, v72
	s_movk_i32 s13, 0xf000
	s_mov_b32 s34, 0x3a800000
	s_mov_b32 s36, 0x358637bd
	s_cbranch_scc1 .LBB0_593
	s_waitcnt vmcnt(5)
	v_xor_b32_e32 v0, 1, v210
	v_cmp_lt_i32_e32 vcc, v0, v250
	s_lshl_b32 s5, s96, 5
	s_lshl_b32 s20, s37, 2
	v_cndmask_b32_e32 v0, v210, v0, vcc
	v_lshlrev_b32_e32 v83, 2, v0
	v_xor_b32_e32 v0, 2, v210
	s_lshl_b32 s4, s56, 2
	v_cmp_lt_i32_e32 vcc, v0, v250
	s_add_i32 s5, s5, s20
	s_add_i32 s20, s5, 0xffff0001
	v_cndmask_b32_e32 v0, v210, v0, vcc
	v_cmp_lt_i32_e32 vcc, v251, v250
	s_ashr_i32 s5, s4, 31
	s_lshl_b32 s26, s33, 5
	v_lshlrev_b32_e32 v84, 2, v0
	v_cndmask_b32_e32 v0, v210, v251, vcc
	s_lshl_b64 s[24:25], s[4:5], 12
	v_lshlrev_b32_e32 v85, 2, v0
	v_xor_b32_e32 v0, 8, v210
	s_add_u32 s42, s10, s24
	v_cmp_lt_i32_e32 vcc, v0, v250
	s_addc_u32 s43, s11, s25
	s_ashr_i32 s27, s26, 31
	v_cndmask_b32_e32 v0, v210, v0, vcc
	s_lshl_b64 s[44:45], s[26:27], 12
	s_lshl_b64 s[4:5], s[4:5], 11
	v_lshlrev_b32_e32 v86, 2, v0
	v_xor_b32_e32 v0, 16, v210
	s_add_u32 s4, s23, s4
	v_cmp_lt_i32_e32 vcc, v0, v250
	s_addc_u32 s5, 0, s5
	v_readlane_b32 s12, v254, 26
	v_cndmask_b32_e32 v0, v210, v0, vcc
	s_add_u32 s24, s12, s78
	v_readlane_b32 s12, v254, 27
	v_lshlrev_b32_e32 v87, 2, v0
	v_xor_b32_e32 v0, 32, v210
	s_addc_u32 s25, s12, s79
	v_cmp_lt_i32_e32 vcc, v0, v250
	s_add_u32 s4, s24, s4
	v_mov_b32_e32 v75, v149
	v_cndmask_b32_e32 v0, v210, v0, vcc
	s_addc_u32 s5, s25, s5
	v_lshlrev_b32_e32 v88, 2, v0
	v_lshl_add_u64 v[78:79], s[4:5], 0, v[74:75]
	s_lshl_b64 s[46:47], s[26:27], 11
	global_load_dwordx4 v[156:159], v[66:67], off
	global_load_dwordx4 v[160:163], v[66:67], off offset:1024
	global_load_dwordx4 v[164:167], v[66:67], off offset:2048
	global_load_dwordx4 v[168:171], v[66:67], off offset:3072
	s_add_u32 s4, s42, 0x1000
	s_addc_u32 s5, s43, 0
	s_add_u32 s24, s42, 0x2000
	s_addc_u32 s25, s43, 0
	s_add_u32 s48, s42, 0x3000
	s_addc_u32 s49, s43, 0
	global_load_dwordx4 v[0:3], v76, s[42:43] nt
	global_load_dwordx4 v[4:7], v76, s[42:43] offset:1024 nt
	global_load_dwordx4 v[8:11], v76, s[42:43] offset:2048 nt
	global_load_dwordx4 v[12:15], v76, s[42:43] offset:3072 nt
	global_load_dwordx4 v[16:19], v76, s[4:5] nt
	global_load_dwordx4 v[20:23], v76, s[4:5] offset:1024 nt
	global_load_dwordx4 v[24:27], v76, s[4:5] offset:2048 nt
	global_load_dwordx4 v[28:31], v76, s[4:5] offset:3072 nt
	global_load_dwordx4 v[32:35], v76, s[24:25] nt
	global_load_dwordx4 v[36:39], v76, s[24:25] offset:1024 nt
	global_load_dwordx4 v[40:43], v76, s[24:25] offset:2048 nt
	global_load_dwordx4 v[44:47], v76, s[24:25] offset:3072 nt
	global_load_dwordx4 v[48:51], v76, s[48:49] nt
	global_load_dwordx4 v[52:55], v76, s[48:49] offset:1024 nt
	global_load_dwordx4 v[56:59], v76, s[48:49] offset:2048 nt
	global_load_dwordx4 v[60:63], v76, s[48:49] offset:3072 nt
	v_bfe_u32 v200, v76, 4, 1
	v_cmp_eq_u32_e64 s[98:99], 0, v200
	v_mul_u32_u24_e32 v200, 0x1f8, v200
	v_mov_b32_e32 v201, 0
	v_lshl_add_u64 v[78:79], v[78:79], 0, v[200:201]
	s_branch .LBB0_557
; DI unsigned pk2(float lo, float hi) { f32x2 v = {lo, hi}; bf16x2_t b = __builtin_convertvector(v, bf16x2_t); return __builtin_bit_cast(unsigned, b); }
; DI void normmod_phase(const float* xl, const float* xc, const float* g, const float* modl  , int cshift, int cscale, bf16_t* H, int nrows, int gw, int NGW, int lane,
;                       const float* part  , const float* pgate  , float* xc_out) {
;     auto ld = [&](const int row, f32x4 (&v)[4]) __attribute__((always_inline)) -> float {
;         const bool lat = row < ML;
;         const float* xr = lat ? xl + (size_t)row * D : xc + (size_t)(row - ML) * D;
;         float ss = 0.f;
; #pragma unroll
;         for (int j = 0; j < 4; ++j) { v[j] = *(const f32x4*)(xr + lane * 4 + 256 * j);
;             if (part && !lat) {
;                 const size_t po = (size_t)(row - ML) * D + lane * 4 + 256 * j;
;                 const f32x4 p0 = *(const f32x4*)(part + po), p1 = *(const f32x4*)(part + (size_t)MC * D + po), p2 = *(const f32x4*)(part + (size_t)2 * MC * D + po), p3 = *(const f32x4*)(part + (size_t)3 * MC * D + po);
;                 v[j] = v[j] + *(const f32x4*)(pgate + lane * 4 + 256 * j) * ((p0 + p1) + (p2 + p3));
;                 *(f32x4*)(xc_out + po) = v[j]; }
;             ss += (v[j][0] * v[j][0] + v[j][1] * v[j][1]) + (v[j][2] * v[j][2] + v[j][3] * v[j][3]); }
;         return ss; };
;     auto st = [&](const int row, const f32x4 (&v)[4], const float rs) __attribute__((always_inline)) {
;         const float* mp = modl + (size_t)((row < ML) ? (row >> 12) : 16) * 6144;
; #pragma unroll
;         for (int j = 0; j < 4; ++j) { const int c = lane * 4 + 256 * j;
;             const f32x4 gg = *(const f32x4*)(g + c), sh = *(const f32x4*)(mp + cshift * 1024 + c), scl = *(const f32x4*)(mp + cscale * 1024 + c);
;             const f32x4 y = (v[j] * rs) * gg * (scl + 1.f) + sh;
;             u32x2 o; o.x = pk2(y[0], y[1]); o.y = pk2(y[2], y[3]);
;             *(u32x2*)(H + (size_t)row * D + c) = o; } };
;     for (int row = gw * 4; row < (nrows < ML ? nrows : ML); row += NGW * 4) {
;         f32x4 vA[4], vB[4], vC[4], vD[4];
;         float sA = ld(row, vA), sB = ld(row + 1, vB), sC = ld(row + 2, vC), sD = ld(row + 3, vD);
; #pragma unroll
;         for (int o = 1; o < 64; o <<= 1) { sA += __shfl_xor(sA, o); sB += __shfl_xor(sB, o); sC += __shfl_xor(sC, o); sD += __shfl_xor(sD, o); }
.LBB0_557:
	s_add_i32 s30, s20, 0xffff
	s_ashr_i32 s30, s30, 12
	s_mul_hi_i32 s31, s30, 0x6000
	s_mulk_i32 s30, 0x6000
	s_add_u32 s50, s16, s30
	s_addc_u32 s51, s17, s31
	s_add_u32 s52, s50, 0x1000
	s_addc_u32 s53, s51, 0
	global_load_dwordx4 v[110:113], v76, s[50:51]
	global_load_dwordx4 v[114:117], v76, s[50:51] offset:1024
	global_load_dwordx4 v[118:121], v76, s[50:51] offset:2048
	global_load_dwordx4 v[122:125], v76, s[50:51] offset:3072
	global_load_dwordx4 v[126:129], v76, s[52:53]
	global_load_dwordx4 v[130:133], v76, s[52:53] offset:1024
	global_load_dwordx4 v[134:137], v76, s[52:53] offset:2048
	global_load_dwordx4 v[138:141], v76, s[52:53] offset:3072
	s_add_i32 s27, s20, s26
	s_add_i32 s27, s27, 0xffff
	s_cmp_gt_i32 s27, 0xffff
	s_cselect_b32 s30, 0, s44
	s_cselect_b32 s31, 0, s45
	s_add_u32 s42, s42, s30
	s_addc_u32 s43, s43, s31
	s_add_u32 s4, s42, 0x1000
	s_addc_u32 s5, s43, 0
	s_add_u32 s24, s42, 0x2000
	s_addc_u32 s25, s43, 0
	s_add_u32 s48, s42, 0x3000
	s_addc_u32 s49, s43, 0
	s_mov_b32 s30, 0xfffff000
	s_mov_b32 s31, -1
	v_mov_b32_e32 v178, s36
	v_lshl_add_u64 v[198:199], v[78:79], 0, s[30:31]
	s_waitcnt vmcnt(20)
	v_mul_f32_e32 v176, v1, v1
	v_mul_f32_e32 v177, v3, v3
	v_fmac_f32_e32 v176, v0, v0
	v_fmac_f32_e32 v177, v2, v2
	v_add_f32_e32 v172, v176, v177
	v_mul_f32_e32 v176, v5, v5
	v_mul_f32_e32 v177, v7, v7
	v_fmac_f32_e32 v176, v4, v4
	v_fmac_f32_e32 v177, v6, v6
	v_add_f32_e32 v176, v176, v177
	v_add_f32_e32 v172, v172, v176
	v_mul_f32_e32 v176, v9, v9
	v_mul_f32_e32 v177, v11, v11
	v_fmac_f32_e32 v176, v8, v8
	v_fmac_f32_e32 v177, v10, v10
	v_add_f32_e32 v176, v176, v177
	v_add_f32_e32 v172, v172, v176
	v_mul_f32_e32 v176, v13, v13
	v_mul_f32_e32 v177, v15, v15
	v_fmac_f32_e32 v176, v12, v12
	v_fmac_f32_e32 v177, v14, v14
	v_add_f32_e32 v176, v176, v177
	v_add_f32_e32 v172, v172, v176
	s_waitcnt vmcnt(16)
	v_mul_f32_e32 v176, v17, v17
	v_mul_f32_e32 v177, v19, v19
	v_fmac_f32_e32 v176, v16, v16
	v_fmac_f32_e32 v177, v18, v18
	v_add_f32_e32 v173, v176, v177
	v_mul_f32_e32 v176, v21, v21
	v_mul_f32_e32 v177, v23, v23
	v_fmac_f32_e32 v176, v20, v20
	v_fmac_f32_e32 v177, v22, v22
	v_add_f32_e32 v176, v176, v177
	v_add_f32_e32 v173, v173, v176
	v_mul_f32_e32 v176, v25, v25
	v_mul_f32_e32 v177, v27, v27
	v_fmac_f32_e32 v176, v24, v24
	v_fmac_f32_e32 v177, v26, v26
	v_add_f32_e32 v176, v176, v177
	v_add_f32_e32 v173, v173, v176
	v_mul_f32_e32 v176, v29, v29
	v_mul_f32_e32 v177, v31, v31
	v_fmac_f32_e32 v176, v28, v28
	v_fmac_f32_e32 v177, v30, v30
	v_add_f32_e32 v176, v176, v177
	v_add_f32_e32 v173, v173, v176
	s_waitcnt vmcnt(12)
	v_mul_f32_e32 v176, v33, v33
	v_mul_f32_e32 v177, v35, v35
	v_fmac_f32_e32 v176, v32, v32
	v_fmac_f32_e32 v177, v34, v34
	v_add_f32_e32 v174, v176, v177
	v_mul_f32_e32 v176, v37, v37
	v_mul_f32_e32 v177, v39, v39
	v_fmac_f32_e32 v176, v36, v36
	v_fmac_f32_e32 v177, v38, v38
	v_add_f32_e32 v176, v176, v177
	v_add_f32_e32 v174, v174, v176
	v_mul_f32_e32 v176, v41, v41
	v_mul_f32_e32 v177, v43, v43
	v_fmac_f32_e32 v176, v40, v40
	v_fmac_f32_e32 v177, v42, v42
	v_add_f32_e32 v176, v176, v177
	v_add_f32_e32 v174, v174, v176
	v_mul_f32_e32 v176, v45, v45
	v_mul_f32_e32 v177, v47, v47
	v_fmac_f32_e32 v176, v44, v44
	v_fmac_f32_e32 v177, v46, v46
	v_add_f32_e32 v176, v176, v177
	v_add_f32_e32 v174, v174, v176
	s_waitcnt vmcnt(8)
	v_mul_f32_e32 v176, v49, v49
	v_mul_f32_e32 v177, v51, v51
	v_fmac_f32_e32 v176, v48, v48
	v_fmac_f32_e32 v177, v50, v50
	v_add_f32_e32 v175, v176, v177
	v_mul_f32_e32 v176, v53, v53
	v_mul_f32_e32 v177, v55, v55
	v_fmac_f32_e32 v176, v52, v52
	v_fmac_f32_e32 v177, v54, v54
	v_add_f32_e32 v176, v176, v177
	v_add_f32_e32 v175, v175, v176
	v_mul_f32_e32 v176, v57, v57
	v_mul_f32_e32 v177, v59, v59
	v_fmac_f32_e32 v176, v56, v56
	v_fmac_f32_e32 v177, v58, v58
	v_add_f32_e32 v176, v176, v177
	v_add_f32_e32 v175, v175, v176
	v_mul_f32_e32 v176, v61, v61
	v_mul_f32_e32 v177, v63, v63
	v_fmac_f32_e32 v176, v60, v60
	v_fmac_f32_e32 v177, v62, v62
	v_add_f32_e32 v176, v176, v177
	v_add_f32_e32 v175, v175, v176
	ds_bpermute_b32 v184, v83, v172
	ds_bpermute_b32 v185, v83, v173
	ds_bpermute_b32 v186, v83, v174
	ds_bpermute_b32 v187, v83, v175
	s_waitcnt lgkmcnt(0)
	v_pk_add_f32 v[172:173], v[172:173], v[184:185]
	v_pk_add_f32 v[174:175], v[174:175], v[186:187]
	ds_bpermute_b32 v184, v84, v172
	ds_bpermute_b32 v185, v84, v173
	ds_bpermute_b32 v186, v84, v174
	ds_bpermute_b32 v187, v84, v175
	s_waitcnt lgkmcnt(0)
	v_pk_add_f32 v[172:173], v[172:173], v[184:185]
	v_pk_add_f32 v[174:175], v[174:175], v[186:187]
	ds_bpermute_b32 v184, v85, v172
	ds_bpermute_b32 v185, v85, v173
	ds_bpermute_b32 v186, v85, v174
	ds_bpermute_b32 v187, v85, v175
	s_waitcnt lgkmcnt(0)
	v_pk_add_f32 v[172:173], v[172:173], v[184:185]
	v_pk_add_f32 v[174:175], v[174:175], v[186:187]
	ds_bpermute_b32 v184, v86, v172
	ds_bpermute_b32 v185, v86, v173
	ds_bpermute_b32 v186, v86, v174
	ds_bpermute_b32 v187, v86, v175
	s_waitcnt lgkmcnt(0)
	v_pk_add_f32 v[172:173], v[172:173], v[184:185]
	v_pk_add_f32 v[174:175], v[174:175], v[186:187]
	ds_bpermute_b32 v184, v87, v172
	ds_bpermute_b32 v185, v87, v173
	ds_bpermute_b32 v186, v87, v174
	ds_bpermute_b32 v187, v87, v175
	s_waitcnt lgkmcnt(0)
	v_pk_add_f32 v[172:173], v[172:173], v[184:185]
	v_pk_add_f32 v[174:175], v[174:175], v[186:187]
	ds_bpermute_b32 v184, v88, v172
	ds_bpermute_b32 v185, v88, v173
	ds_bpermute_b32 v186, v88, v174
	ds_bpermute_b32 v187, v88, v175
	s_waitcnt lgkmcnt(0)
; DI unsigned pk2(float lo, float hi) { f32x2 v = {lo, hi}; bf16x2_t b = __builtin_convertvector(v, bf16x2_t); return __builtin_bit_cast(unsigned, b); }
; DI void normmod_phase(const float* xl, const float* xc, const float* g, const float* modl  , int cshift, int cscale, bf16_t* H, int nrows, int gw, int NGW, int lane,
;                       const float* part  , const float* pgate  , float* xc_out) {
;     ...
;     auto st = [&](const int row, const f32x4 (&v)[4], const float rs) __attribute__((always_inline)) {
;         const float* mp = modl + (size_t)((row < ML) ? (row >> 12) : 16) * 6144;
; #pragma unroll
;         for (int j = 0; j < 4; ++j) { const int c = lane * 4 + 256 * j;
;             const f32x4 gg = *(const f32x4*)(g + c), sh = *(const f32x4*)(mp + cshift * 1024 + c), scl = *(const f32x4*)(mp + cscale * 1024 + c);
;             const f32x4 y = (v[j] * rs) * gg * (scl + 1.f) + sh;
;             u32x2 o; o.x = pk2(y[0], y[1]); o.y = pk2(y[2], y[3]);
;             *(u32x2*)(H + (size_t)row * D + c) = o; } };
;     for (int row = gw * 4; row < (nrows < ML ? nrows : ML); row += NGW * 4) {
;         f32x4 vA[4], vB[4], vC[4], vD[4];
;         float sA = ld(row, vA), sB = ld(row + 1, vB), sC = ld(row + 2, vC), sD = ld(row + 3, vD);
; #pragma unroll
;         for (int o = 1; o < 64; o <<= 1) { sA += __shfl_xor(sA, o); sB += __shfl_xor(sB, o); sC += __shfl_xor(sC, o); sD += __shfl_xor(sD, o); }
;         st(row, vA, rsqrtf(sA * (1.f / D) + EPS)); st(row + 1, vB, rsqrtf(sB * (1.f / D) + EPS));
;         st(row + 2, vC, rsqrtf(sC * (1.f / D) + EPS)); st(row + 3, vD, rsqrtf(sD * (1.f / D) + EPS));
	v_pk_add_f32 v[172:173], v[172:173], v[184:185]
	v_pk_add_f32 v[174:175], v[174:175], v[186:187]
	v_fma_f32 v172, v172, s34, v178
	v_fma_f32 v173, v173, s34, v178
	v_fma_f32 v174, v174, s34, v178
	v_fma_f32 v175, v175, s34, v178
	v_mul_f32_e32 v184, 0x4b800000, v172
	v_mul_f32_e32 v185, 0x4b800000, v173
	v_mul_f32_e32 v186, 0x4b800000, v174
	v_mul_f32_e32 v187, 0x4b800000, v175
	s_waitcnt vmcnt(0)
	v_cmp_gt_f32_e64 s[50:51], s62, v172
	v_cmp_gt_f32_e64 s[52:53], s62, v173
	v_cmp_gt_f32_e64 s[30:31], s62, v174
	v_cmp_gt_f32_e32 vcc, s62, v175
	s_nop 1
	v_cndmask_b32_e64 v172, v172, v184, s[50:51]
	v_cndmask_b32_e64 v173, v173, v185, s[52:53]
	v_cndmask_b32_e64 v174, v174, v186, s[30:31]
	v_cndmask_b32_e32 v175, v175, v187, vcc
	v_rsq_f32_e32 v172, v172
	v_rsq_f32_e32 v173, v173
	v_rsq_f32_e32 v174, v174
	v_rsq_f32_e32 v175, v175
	s_nop 0
	v_mul_f32_e32 v184, 0x45800000, v172
	v_mul_f32_e32 v185, 0x45800000, v173
	v_mul_f32_e32 v186, 0x45800000, v174
	v_mul_f32_e32 v187, 0x45800000, v175
	v_cndmask_b32_e64 v188, v172, v184, s[50:51]
	v_cndmask_b32_e64 v190, v173, v185, s[52:53]
	v_cndmask_b32_e64 v192, v174, v186, s[30:31]
	v_cndmask_b32_e32 v194, v175, v187, vcc
	v_pk_add_f32 v[126:127], v[126:127], 1.0 op_sel_hi:[1,0]
	v_pk_add_f32 v[128:129], v[128:129], 1.0 op_sel_hi:[1,0]
	v_pk_add_f32 v[130:131], v[130:131], 1.0 op_sel_hi:[1,0]
	v_pk_add_f32 v[132:133], v[132:133], 1.0 op_sel_hi:[1,0]
	v_pk_add_f32 v[134:135], v[134:135], 1.0 op_sel_hi:[1,0]
	v_pk_add_f32 v[136:137], v[136:137], 1.0 op_sel_hi:[1,0]
	v_pk_add_f32 v[138:139], v[138:139], 1.0 op_sel_hi:[1,0]
	v_pk_add_f32 v[140:141], v[140:141], 1.0 op_sel_hi:[1,0]
	v_pk_mul_f32 v[0:1], v[0:1], v[188:189] op_sel_hi:[1,0]
	v_pk_mul_f32 v[2:3], v[2:3], v[188:189] op_sel_hi:[1,0]
	v_pk_mul_f32 v[0:1], v[156:157], v[0:1]
	v_pk_mul_f32 v[2:3], v[158:159], v[2:3]
	v_pk_fma_f32 v[0:1], v[126:127], v[0:1], v[110:111]
	v_pk_fma_f32 v[2:3], v[128:129], v[2:3], v[112:113]
	v_pk_mul_f32 v[4:5], v[4:5], v[188:189] op_sel_hi:[1,0]
	v_pk_mul_f32 v[6:7], v[6:7], v[188:189] op_sel_hi:[1,0]
	v_pk_mul_f32 v[4:5], v[160:161], v[4:5]
	v_pk_mul_f32 v[6:7], v[162:163], v[6:7]
	v_pk_fma_f32 v[4:5], v[130:131], v[4:5], v[114:115]
	v_pk_fma_f32 v[6:7], v[132:133], v[6:7], v[116:117]
	v_pk_mul_f32 v[8:9], v[8:9], v[188:189] op_sel_hi:[1,0]
	v_pk_mul_f32 v[10:11], v[10:11], v[188:189] op_sel_hi:[1,0]
	v_pk_mul_f32 v[8:9], v[164:165], v[8:9]
	v_pk_mul_f32 v[10:11], v[166:167], v[10:11]
	v_pk_fma_f32 v[8:9], v[134:135], v[8:9], v[118:119]
	v_pk_fma_f32 v[10:11], v[136:137], v[10:11], v[120:121]
	v_pk_mul_f32 v[12:13], v[12:13], v[188:189] op_sel_hi:[1,0]
	v_pk_mul_f32 v[14:15], v[14:15], v[188:189] op_sel_hi:[1,0]
	v_pk_mul_f32 v[12:13], v[168:169], v[12:13]
	v_pk_mul_f32 v[14:15], v[170:171], v[14:15]
	v_pk_fma_f32 v[12:13], v[138:139], v[12:13], v[122:123]
	v_pk_fma_f32 v[14:15], v[140:141], v[14:15], v[124:125]
	v_cvt_pk_bf16_f32 v0, v0, v1
	v_cvt_pk_bf16_f32 v1, v2, v3
	v_cvt_pk_bf16_f32 v4, v4, v5
	v_cvt_pk_bf16_f32 v5, v6, v7
	v_cvt_pk_bf16_f32 v8, v8, v9
	v_cvt_pk_bf16_f32 v9, v10, v11
	v_cvt_pk_bf16_f32 v12, v12, v13
	v_cvt_pk_bf16_f32 v13, v14, v15
	v_mov_b32_dpp v2, v0 quad_perm:[1,0,3,2] row_mask:0xf bank_mask:0xf
	v_mov_b32_dpp v3, v1 quad_perm:[1,0,3,2] row_mask:0xf bank_mask:0xf
	v_mov_b32_dpp v176, v4 quad_perm:[1,0,3,2] row_mask:0xf bank_mask:0xf
	v_mov_b32_dpp v177, v5 quad_perm:[1,0,3,2] row_mask:0xf bank_mask:0xf
	v_cndmask_b32_e64 v2, v4, v2, s[98:99]
	v_cndmask_b32_e64 v3, v5, v3, s[98:99]
	v_cndmask_b32_e64 v0, v176, v0, s[98:99]
	v_cndmask_b32_e64 v1, v177, v1, s[98:99]
	global_store_dwordx4 v[198:199], v[0:3], off offset:-3584
	v_mov_b32_dpp v10, v8 quad_perm:[1,0,3,2] row_mask:0xf bank_mask:0xf
	v_mov_b32_dpp v11, v9 quad_perm:[1,0,3,2] row_mask:0xf bank_mask:0xf
	v_mov_b32_dpp v176, v12 quad_perm:[1,0,3,2] row_mask:0xf bank_mask:0xf
	v_mov_b32_dpp v177, v13 quad_perm:[1,0,3,2] row_mask:0xf bank_mask:0xf
	v_cndmask_b32_e64 v10, v12, v10, s[98:99]
	v_cndmask_b32_e64 v11, v13, v11, s[98:99]
	v_cndmask_b32_e64 v8, v176, v8, s[98:99]
	v_cndmask_b32_e64 v9, v177, v9, s[98:99]
	global_store_dwordx4 v[198:199], v[8:11], off offset:-2560
	global_load_dwordx4 v[0:3], v76, s[42:43] nt
	global_load_dwordx4 v[4:7], v76, s[42:43] offset:1024 nt
	global_load_dwordx4 v[8:11], v76, s[42:43] offset:2048 nt
	global_load_dwordx4 v[12:15], v76, s[42:43] offset:3072 nt
	v_pk_mul_f32 v[16:17], v[16:17], v[190:191] op_sel_hi:[1,0]
	v_pk_mul_f32 v[18:19], v[18:19], v[190:191] op_sel_hi:[1,0]
	v_pk_mul_f32 v[16:17], v[156:157], v[16:17]
	v_pk_mul_f32 v[18:19], v[158:159], v[18:19]
	v_pk_fma_f32 v[16:17], v[126:127], v[16:17], v[110:111]
	v_pk_fma_f32 v[18:19], v[128:129], v[18:19], v[112:113]
	v_pk_mul_f32 v[20:21], v[20:21], v[190:191] op_sel_hi:[1,0]
	v_pk_mul_f32 v[22:23], v[22:23], v[190:191] op_sel_hi:[1,0]
	v_pk_mul_f32 v[20:21], v[160:161], v[20:21]
	v_pk_mul_f32 v[22:23], v[162:163], v[22:23]
	v_pk_fma_f32 v[20:21], v[130:131], v[20:21], v[114:115]
	v_pk_fma_f32 v[22:23], v[132:133], v[22:23], v[116:117]
	v_pk_mul_f32 v[24:25], v[24:25], v[190:191] op_sel_hi:[1,0]
	v_pk_mul_f32 v[26:27], v[26:27], v[190:191] op_sel_hi:[1,0]
	v_pk_mul_f32 v[24:25], v[164:165], v[24:25]
	v_pk_mul_f32 v[26:27], v[166:167], v[26:27]
	v_pk_fma_f32 v[24:25], v[134:135], v[24:25], v[118:119]
	v_pk_fma_f32 v[26:27], v[136:137], v[26:27], v[120:121]
	v_pk_mul_f32 v[28:29], v[28:29], v[190:191] op_sel_hi:[1,0]
	v_pk_mul_f32 v[30:31], v[30:31], v[190:191] op_sel_hi:[1,0]
	v_pk_mul_f32 v[28:29], v[168:169], v[28:29]
	v_pk_mul_f32 v[30:31], v[170:171], v[30:31]
	v_pk_fma_f32 v[28:29], v[138:139], v[28:29], v[122:123]
; DI unsigned pk2(float lo, float hi) { f32x2 v = {lo, hi}; bf16x2_t b = __builtin_convertvector(v, bf16x2_t); return __builtin_bit_cast(unsigned, b); }
; DI void normmod_phase(const float* xl, const float* xc, const float* g, const float* modl  , int cshift, int cscale, bf16_t* H, int nrows, int gw, int NGW, int lane,
;                       const float* part  , const float* pgate  , float* xc_out) {
;     ...
;     auto st = [&](const int row, const f32x4 (&v)[4], const float rs) __attribute__((always_inline)) {
;         const float* mp = modl + (size_t)((row < ML) ? (row >> 12) : 16) * 6144;
; #pragma unroll
;         for (int j = 0; j < 4; ++j) { const int c = lane * 4 + 256 * j;
;             const f32x4 gg = *(const f32x4*)(g + c), sh = *(const f32x4*)(mp + cshift * 1024 + c), scl = *(const f32x4*)(mp + cscale * 1024 + c);
;             const f32x4 y = (v[j] * rs) * gg * (scl + 1.f) + sh;
;             u32x2 o; o.x = pk2(y[0], y[1]); o.y = pk2(y[2], y[3]);
;             *(u32x2*)(H + (size_t)row * D + c) = o; } };
	v_pk_fma_f32 v[30:31], v[140:141], v[30:31], v[124:125]
	v_cvt_pk_bf16_f32 v16, v16, v17
	v_cvt_pk_bf16_f32 v17, v18, v19
	v_cvt_pk_bf16_f32 v20, v20, v21
	v_cvt_pk_bf16_f32 v21, v22, v23
	v_cvt_pk_bf16_f32 v24, v24, v25
	v_cvt_pk_bf16_f32 v25, v26, v27
	v_cvt_pk_bf16_f32 v28, v28, v29
	v_cvt_pk_bf16_f32 v29, v30, v31
	v_mov_b32_dpp v18, v16 quad_perm:[1,0,3,2] row_mask:0xf bank_mask:0xf
	v_mov_b32_dpp v19, v17 quad_perm:[1,0,3,2] row_mask:0xf bank_mask:0xf
	v_mov_b32_dpp v176, v20 quad_perm:[1,0,3,2] row_mask:0xf bank_mask:0xf
	v_mov_b32_dpp v177, v21 quad_perm:[1,0,3,2] row_mask:0xf bank_mask:0xf
	v_cndmask_b32_e64 v18, v20, v18, s[98:99]
	v_cndmask_b32_e64 v19, v21, v19, s[98:99]
	v_cndmask_b32_e64 v16, v176, v16, s[98:99]
	v_cndmask_b32_e64 v17, v177, v17, s[98:99]
	global_store_dwordx4 v[198:199], v[16:19], off offset:-1536
	v_mov_b32_dpp v26, v24 quad_perm:[1,0,3,2] row_mask:0xf bank_mask:0xf
	v_mov_b32_dpp v27, v25 quad_perm:[1,0,3,2] row_mask:0xf bank_mask:0xf
	v_mov_b32_dpp v176, v28 quad_perm:[1,0,3,2] row_mask:0xf bank_mask:0xf
	v_mov_b32_dpp v177, v29 quad_perm:[1,0,3,2] row_mask:0xf bank_mask:0xf
	v_cndmask_b32_e64 v26, v28, v26, s[98:99]
	v_cndmask_b32_e64 v27, v29, v27, s[98:99]
	v_cndmask_b32_e64 v24, v176, v24, s[98:99]
	v_cndmask_b32_e64 v25, v177, v25, s[98:99]
	global_store_dwordx4 v[198:199], v[24:27], off offset:-512
	global_load_dwordx4 v[16:19], v76, s[4:5] nt
	global_load_dwordx4 v[20:23], v76, s[4:5] offset:1024 nt
	global_load_dwordx4 v[24:27], v76, s[4:5] offset:2048 nt
	global_load_dwordx4 v[28:31], v76, s[4:5] offset:3072 nt
	v_pk_mul_f32 v[32:33], v[32:33], v[192:193] op_sel_hi:[1,0]
	v_pk_mul_f32 v[34:35], v[34:35], v[192:193] op_sel_hi:[1,0]
	v_pk_mul_f32 v[32:33], v[156:157], v[32:33]
	v_pk_mul_f32 v[34:35], v[158:159], v[34:35]
	v_pk_fma_f32 v[32:33], v[126:127], v[32:33], v[110:111]
	v_pk_fma_f32 v[34:35], v[128:129], v[34:35], v[112:113]
	v_pk_mul_f32 v[36:37], v[36:37], v[192:193] op_sel_hi:[1,0]
	v_pk_mul_f32 v[38:39], v[38:39], v[192:193] op_sel_hi:[1,0]
	v_pk_mul_f32 v[36:37], v[160:161], v[36:37]
	v_pk_mul_f32 v[38:39], v[162:163], v[38:39]
	v_pk_fma_f32 v[36:37], v[130:131], v[36:37], v[114:115]
	v_pk_fma_f32 v[38:39], v[132:133], v[38:39], v[116:117]
	v_pk_mul_f32 v[40:41], v[40:41], v[192:193] op_sel_hi:[1,0]
	v_pk_mul_f32 v[42:43], v[42:43], v[192:193] op_sel_hi:[1,0]
	v_pk_mul_f32 v[40:41], v[164:165], v[40:41]
	v_pk_mul_f32 v[42:43], v[166:167], v[42:43]
	v_pk_fma_f32 v[40:41], v[134:135], v[40:41], v[118:119]
	v_pk_fma_f32 v[42:43], v[136:137], v[42:43], v[120:121]
	v_pk_mul_f32 v[44:45], v[44:45], v[192:193] op_sel_hi:[1,0]
	v_pk_mul_f32 v[46:47], v[46:47], v[192:193] op_sel_hi:[1,0]
	v_pk_mul_f32 v[44:45], v[168:169], v[44:45]
	v_pk_mul_f32 v[46:47], v[170:171], v[46:47]
	v_pk_fma_f32 v[44:45], v[138:139], v[44:45], v[122:123]
	v_pk_fma_f32 v[46:47], v[140:141], v[46:47], v[124:125]
	v_cvt_pk_bf16_f32 v32, v32, v33
	v_cvt_pk_bf16_f32 v33, v34, v35
	v_cvt_pk_bf16_f32 v36, v36, v37
	v_cvt_pk_bf16_f32 v37, v38, v39
	v_cvt_pk_bf16_f32 v40, v40, v41
	v_cvt_pk_bf16_f32 v41, v42, v43
	v_cvt_pk_bf16_f32 v44, v44, v45
	v_cvt_pk_bf16_f32 v45, v46, v47
	v_mov_b32_dpp v34, v32 quad_perm:[1,0,3,2] row_mask:0xf bank_mask:0xf
	v_mov_b32_dpp v35, v33 quad_perm:[1,0,3,2] row_mask:0xf bank_mask:0xf
	v_mov_b32_dpp v176, v36 quad_perm:[1,0,3,2] row_mask:0xf bank_mask:0xf
	v_mov_b32_dpp v177, v37 quad_perm:[1,0,3,2] row_mask:0xf bank_mask:0xf
	v_cndmask_b32_e64 v34, v36, v34, s[98:99]
	v_cndmask_b32_e64 v35, v37, v35, s[98:99]
	v_cndmask_b32_e64 v32, v176, v32, s[98:99]
	v_cndmask_b32_e64 v33, v177, v33, s[98:99]
	global_store_dwordx4 v[78:79], v[32:35], off offset:-3584
	v_mov_b32_dpp v42, v40 quad_perm:[1,0,3,2] row_mask:0xf bank_mask:0xf
; DI unsigned pk2(float lo, float hi) { f32x2 v = {lo, hi}; bf16x2_t b = __builtin_convertvector(v, bf16x2_t); return __builtin_bit_cast(unsigned, b); }
; DI void normmod_phase(const float* xl, const float* xc, const float* g, const float* modl  , int cshift, int cscale, bf16_t* H, int nrows, int gw, int NGW, int lane,
;                       const float* part  , const float* pgate  , float* xc_out) {
;     ...
;     auto st = [&](const int row, const f32x4 (&v)[4], const float rs) __attribute__((always_inline)) {
;         const float* mp = modl + (size_t)((row < ML) ? (row >> 12) : 16) * 6144;
; #pragma unroll
;         for (int j = 0; j < 4; ++j) { const int c = lane * 4 + 256 * j;
;             const f32x4 gg = *(const f32x4*)(g + c), sh = *(const f32x4*)(mp + cshift * 1024 + c), scl = *(const f32x4*)(mp + cscale * 1024 + c);
;             const f32x4 y = (v[j] * rs) * gg * (scl + 1.f) + sh;
;             u32x2 o; o.x = pk2(y[0], y[1]); o.y = pk2(y[2], y[3]);
;             *(u32x2*)(H + (size_t)row * D + c) = o; } };
;     for (int row = gw * 4; row < (nrows < ML ? nrows : ML); row += NGW * 4) {
;         f32x4 vA[4], vB[4], vC[4], vD[4];
;         float sA = ld(row, vA), sB = ld(row + 1, vB), sC = ld(row + 2, vC), sD = ld(row + 3, vD);
; #pragma unroll
;         for (int o = 1; o < 64; o <<= 1) { sA += __shfl_xor(sA, o); sB += __shfl_xor(sB, o); sC += __shfl_xor(sC, o); sD += __shfl_xor(sD, o); }
;         st(row, vA, rsqrtf(sA * (1.f / D) + EPS)); st(row + 1, vB, rsqrtf(sB * (1.f / D) + EPS));
;         st(row + 2, vC, rsqrtf(sC * (1.f / D) + EPS)); st(row + 3, vD, rsqrtf(sD * (1.f / D) + EPS));
	v_mov_b32_dpp v43, v41 quad_perm:[1,0,3,2] row_mask:0xf bank_mask:0xf
	v_mov_b32_dpp v176, v44 quad_perm:[1,0,3,2] row_mask:0xf bank_mask:0xf
	v_mov_b32_dpp v177, v45 quad_perm:[1,0,3,2] row_mask:0xf bank_mask:0xf
	v_cndmask_b32_e64 v42, v44, v42, s[98:99]
	v_cndmask_b32_e64 v43, v45, v43, s[98:99]
	v_cndmask_b32_e64 v40, v176, v40, s[98:99]
	v_cndmask_b32_e64 v41, v177, v41, s[98:99]
	global_store_dwordx4 v[78:79], v[40:43], off offset:-2560
	global_load_dwordx4 v[32:35], v76, s[24:25] nt
	global_load_dwordx4 v[36:39], v76, s[24:25] offset:1024 nt
	global_load_dwordx4 v[40:43], v76, s[24:25] offset:2048 nt
	global_load_dwordx4 v[44:47], v76, s[24:25] offset:3072 nt
	v_pk_mul_f32 v[48:49], v[48:49], v[194:195] op_sel_hi:[1,0]
	v_pk_mul_f32 v[50:51], v[50:51], v[194:195] op_sel_hi:[1,0]
	v_pk_mul_f32 v[48:49], v[156:157], v[48:49]
	v_pk_mul_f32 v[50:51], v[158:159], v[50:51]
	v_pk_fma_f32 v[48:49], v[126:127], v[48:49], v[110:111]
	v_pk_fma_f32 v[50:51], v[128:129], v[50:51], v[112:113]
	v_pk_mul_f32 v[52:53], v[52:53], v[194:195] op_sel_hi:[1,0]
	v_pk_mul_f32 v[54:55], v[54:55], v[194:195] op_sel_hi:[1,0]
	v_pk_mul_f32 v[52:53], v[160:161], v[52:53]
	v_pk_mul_f32 v[54:55], v[162:163], v[54:55]
	v_pk_fma_f32 v[52:53], v[130:131], v[52:53], v[114:115]
	v_pk_fma_f32 v[54:55], v[132:133], v[54:55], v[116:117]
	v_pk_mul_f32 v[56:57], v[56:57], v[194:195] op_sel_hi:[1,0]
	v_pk_mul_f32 v[58:59], v[58:59], v[194:195] op_sel_hi:[1,0]
	v_pk_mul_f32 v[56:57], v[164:165], v[56:57]
	v_pk_mul_f32 v[58:59], v[166:167], v[58:59]
	v_pk_fma_f32 v[56:57], v[134:135], v[56:57], v[118:119]
	v_pk_fma_f32 v[58:59], v[136:137], v[58:59], v[120:121]
	v_pk_mul_f32 v[60:61], v[60:61], v[194:195] op_sel_hi:[1,0]
	v_pk_mul_f32 v[62:63], v[62:63], v[194:195] op_sel_hi:[1,0]
	v_pk_mul_f32 v[60:61], v[168:169], v[60:61]
	v_pk_mul_f32 v[62:63], v[170:171], v[62:63]
	v_pk_fma_f32 v[60:61], v[138:139], v[60:61], v[122:123]
	v_pk_fma_f32 v[62:63], v[140:141], v[62:63], v[124:125]
	v_cvt_pk_bf16_f32 v48, v48, v49
	v_cvt_pk_bf16_f32 v49, v50, v51
	v_cvt_pk_bf16_f32 v52, v52, v53
	v_cvt_pk_bf16_f32 v53, v54, v55
	v_cvt_pk_bf16_f32 v56, v56, v57
	v_cvt_pk_bf16_f32 v57, v58, v59
	v_cvt_pk_bf16_f32 v60, v60, v61
	v_cvt_pk_bf16_f32 v61, v62, v63
	v_mov_b32_dpp v50, v48 quad_perm:[1,0,3,2] row_mask:0xf bank_mask:0xf
	v_mov_b32_dpp v51, v49 quad_perm:[1,0,3,2] row_mask:0xf bank_mask:0xf
	v_mov_b32_dpp v176, v52 quad_perm:[1,0,3,2] row_mask:0xf bank_mask:0xf
	v_mov_b32_dpp v177, v53 quad_perm:[1,0,3,2] row_mask:0xf bank_mask:0xf
	v_cndmask_b32_e64 v50, v52, v50, s[98:99]
	v_cndmask_b32_e64 v51, v53, v51, s[98:99]
	v_cndmask_b32_e64 v48, v176, v48, s[98:99]
	v_cndmask_b32_e64 v49, v177, v49, s[98:99]
	global_store_dwordx4 v[78:79], v[48:51], off offset:-1536
	v_mov_b32_dpp v58, v56 quad_perm:[1,0,3,2] row_mask:0xf bank_mask:0xf
	v_mov_b32_dpp v59, v57 quad_perm:[1,0,3,2] row_mask:0xf bank_mask:0xf
	v_mov_b32_dpp v176, v60 quad_perm:[1,0,3,2] row_mask:0xf bank_mask:0xf
	v_mov_b32_dpp v177, v61 quad_perm:[1,0,3,2] row_mask:0xf bank_mask:0xf
	v_cndmask_b32_e64 v58, v60, v58, s[98:99]
	v_cndmask_b32_e64 v59, v61, v59, s[98:99]
	v_cndmask_b32_e64 v56, v176, v56, s[98:99]
	v_cndmask_b32_e64 v57, v177, v57, s[98:99]
	global_store_dwordx4 v[78:79], v[56:59], off offset:-512
	global_load_dwordx4 v[48:51], v76, s[48:49] nt
	global_load_dwordx4 v[52:55], v76, s[48:49] offset:1024 nt
	global_load_dwordx4 v[56:59], v76, s[48:49] offset:2048 nt
	global_load_dwordx4 v[60:63], v76, s[48:49] offset:3072 nt
	s_add_i32 s20, s20, s26
	v_lshl_add_u64 v[78:79], v[78:79], 0, s[46:47]
	s_add_i32 s4, s20, 0xffff
	s_cmp_gt_i32 s4, 0xffff
	s_cbranch_scc0 .LBB0_557
	s_waitcnt vmcnt(0)
